# P12 post_rows: next trip's y-row loads issued during the current trip; early drain replaced by a counted wait before the first x use
# baseline (speedup 1.0000x reference)
.LBB0_1488:
	s_cmp_lt_i32 s44, 13
	s_cselect_b64 s[4:5], -1, 0
	s_and_b64 s[4:5], s[4:5], s[6:7]
	s_andn2_b64 vcc, exec, s[4:5]
	s_cbranch_vccnz .LBB0_1492
	v_and_b32_e32 v0, 30, v198
	v_lshl_add_u32 v48, s2, 4, v0
	s_movk_i32 s2, 0x4000
	v_cmp_gt_i32_e32 vcc, s2, v48
	s_and_saveexec_b64 s[2:3], vcc
	s_cbranch_execz .LBB0_1492
	s_load_dwordx2 s[0:1], s[0:1], 0xc0
	v_lshlrev_b32_e32 v0, 2, v213
	v_and_b32_e32 v36, 0xfc, v0
	v_mov_b32_e32 v33, 0
	v_lshlrev_b32_e32 v32, 2, v36
	s_waitcnt lgkmcnt(0)
	v_lshl_add_u64 v[16:17], s[0:1], 0, v[32:33]
	v_add_co_u32_e32 v34, vcc, 0x1000, v16
	global_load_dwordx4 v[0:3], v32, s[0:1]
	global_load_dwordx4 v[4:7], v32, s[0:1] offset:1024
	global_load_dwordx4 v[8:11], v32, s[0:1] offset:2048
	global_load_dwordx4 v[12:15], v32, s[0:1] offset:3072
	v_addc_co_u32_e32 v35, vcc, 0, v17, vcc
	global_load_dwordx4 v[16:19], v[34:35], off
	global_load_dwordx4 v[20:23], v[34:35], off offset:1024
	global_load_dwordx4 v[24:27], v[34:35], off offset:2048
	global_load_dwordx4 v[28:31], v[34:35], off offset:3072
	v_lshl_add_u64 v[52:53], s[40:41], 0, v[32:33]
	v_mbcnt_lo_u32_b32 v32, -1, 0
	v_lshlrev_b32_e32 v34, 1, v36
	v_mov_b32_e32 v35, v33
	v_mbcnt_hi_u32_b32 v32, -1, v32
	v_lshl_add_u64 v[34:35], s[42:43], 0, v[34:35]
	s_mov_b64 s[0:1], 0x14804000
	v_and_b32_e32 v33, 64, v32
	v_lshl_add_u64 v[50:51], v[34:35], 0, s[0:1]
	v_add_u32_e32 v33, 64, v33
	v_xor_b32_e32 v34, 32, v32
	v_cmp_lt_i32_e32 vcc, v34, v33
	s_movk_i32 s3, 0x1000
	s_lshl_b32 s4, s46, 4
	v_cndmask_b32_e32 v34, v32, v34, vcc
	v_lshlrev_b32_e32 v55, 2, v34
	v_xor_b32_e32 v34, 16, v32
	v_cmp_lt_i32_e32 vcc, v34, v33
	s_mov_b64 s[0:1], 0
	s_mov_b32 s2, 0x3a000000
	v_cndmask_b32_e32 v34, v32, v34, vcc
	v_lshlrev_b32_e32 v124, 2, v34
	v_xor_b32_e32 v34, 8, v32
	v_cmp_lt_i32_e32 vcc, v34, v33
	s_mov_b32 s5, 0x800000
	s_movk_i32 s6, 0x3fff
	v_cndmask_b32_e32 v34, v32, v34, vcc
	v_lshlrev_b32_e32 v125, 2, v34
	v_xor_b32_e32 v34, 4, v32
	v_cmp_lt_i32_e32 vcc, v34, v33
	v_mov_b32_e32 v54, 0x358637bd
	s_nop 0
	v_cndmask_b32_e32 v34, v32, v34, vcc
	v_lshlrev_b32_e32 v126, 2, v34
	v_xor_b32_e32 v34, 2, v32
	v_cmp_lt_i32_e32 vcc, v34, v33
	s_nop 1
	v_cndmask_b32_e32 v34, v32, v34, vcc
	v_lshlrev_b32_e32 v127, 2, v34
	v_xor_b32_e32 v34, 1, v32
	v_cmp_lt_i32_e32 vcc, v34, v33
	s_nop 1
	v_cndmask_b32_e32 v32, v32, v34, vcc
	v_lshlrev_b32_e32 v128, 2, v32
	s_mov_b32 s100, 0x1000
	s_mov_b32 s101, 0
	v_mov_b32_e32 v246, v48
	v_ashrrev_i32_e32 v247, 31, v246
	v_lshlrev_b64 v[248:249], 12, v[246:247]
	v_lshl_add_u64 v[248:249], v[50:51], 0, v[248:249]
	v_lshl_add_u64 v[250:251], v[248:249], 0, s[100:101]
	global_load_dwordx2 v[214:215], v[248:249], off offset:2560 nt
	global_load_dwordx2 v[216:217], v[248:249], off offset:2048 nt
	global_load_dwordx2 v[218:219], v[248:249], off offset:3584 nt
	global_load_dwordx2 v[220:221], v[248:249], off offset:3072 nt
	global_load_dwordx2 v[222:223], v[248:249], off nt
	global_load_dwordx2 v[224:225], v[248:249], off offset:512 nt
	global_load_dwordx2 v[226:227], v[248:249], off offset:1024 nt
	global_load_dwordx2 v[228:229], v[250:251], off offset:2560 nt
	global_load_dwordx2 v[230:231], v[250:251], off offset:2048 nt
	global_load_dwordx2 v[232:233], v[250:251], off nt
	global_load_dwordx2 v[234:235], v[250:251], off offset:512 nt
	global_load_dwordx2 v[236:237], v[250:251], off offset:1024 nt
	global_load_dwordx2 v[238:239], v[250:251], off offset:1536 nt
	global_load_dwordx2 v[240:241], v[248:249], off offset:1536 nt
	global_load_dwordx2 v[242:243], v[250:251], off offset:3072 nt
	global_load_dwordx2 v[244:245], v[250:251], off offset:3584 nt
	s_waitcnt vmcnt(0)
.LBB0_1491:
	v_ashrrev_i32_e32 v49, 31, v48
	v_lshlrev_b64 v[32:33], 12, v[48:49]
	v_lshl_add_u64 v[32:33], v[50:51], 0, v[32:33]
	v_add_u32_e32 v44, 1, v48
	v_mov_b64_e32 v[46:47], v[214:215]
	v_mov_b64_e32 v[56:57], v[216:217]
	v_mov_b64_e32 v[58:59], v[218:219]
	v_mov_b64_e32 v[60:61], v[220:221]
	v_mov_b64_e32 v[62:63], v[222:223]
	v_mov_b64_e32 v[76:77], v[224:225]
	v_mov_b64_e32 v[104:105], v[226:227]
	v_ashrrev_i32_e32 v45, 31, v44
	v_lshlrev_b64 v[34:35], 12, v[44:45]
	v_lshl_add_u64 v[64:65], v[50:51], 0, v[34:35]
	v_mov_b64_e32 v[106:107], v[228:229]
	v_mov_b64_e32 v[108:109], v[230:231]
	v_mov_b64_e32 v[110:111], v[232:233]
	v_mov_b64_e32 v[112:113], v[234:235]
	v_mov_b64_e32 v[114:115], v[236:237]
	v_mov_b64_e32 v[122:123], v[238:239]
	v_mov_b64_e32 v[120:121], v[240:241]
	v_lshlrev_b64 v[32:33], 13, v[48:49]
	v_lshl_add_u64 v[100:101], v[52:53], 0, v[32:33]
	global_load_dwordx4 v[40:43], v[100:101], off nt
	global_load_dwordx4 v[36:39], v[100:101], off offset:1024 nt
	global_load_dwordx4 v[32:35], v[100:101], off offset:2048 nt
	v_mov_b64_e32 v[130:131], v[242:243]
	v_mov_b64_e32 v[132:133], v[244:245]
	v_add_co_u32_e32 v178, vcc, s3, v100
	v_lshlrev_b64 v[44:45], 13, v[44:45]
	s_nop 0
	v_addc_co_u32_e32 v179, vcc, 0, v101, vcc
	v_lshl_add_u64 v[180:181], v[52:53], 0, v[44:45]
	v_add_u32_e32 v48, s4, v48
	v_min_i32_e32 v246, 0x3ffe, v48
	v_ashrrev_i32_e32 v247, 31, v246
	v_lshlrev_b64 v[248:249], 12, v[246:247]
	v_lshl_add_u64 v[248:249], v[50:51], 0, v[248:249]
	v_lshl_add_u64 v[250:251], v[248:249], 0, s[100:101]
	global_load_dwordx2 v[214:215], v[248:249], off offset:2560 nt
	global_load_dwordx2 v[216:217], v[248:249], off offset:2048 nt
	global_load_dwordx2 v[218:219], v[248:249], off offset:3584 nt
	global_load_dwordx2 v[220:221], v[248:249], off offset:3072 nt
	global_load_dwordx2 v[222:223], v[248:249], off nt
	global_load_dwordx2 v[224:225], v[248:249], off offset:512 nt
	global_load_dwordx2 v[226:227], v[248:249], off offset:1024 nt
	global_load_dwordx2 v[228:229], v[250:251], off offset:2560 nt
	global_load_dwordx2 v[230:231], v[250:251], off offset:2048 nt
	global_load_dwordx2 v[232:233], v[250:251], off nt
	global_load_dwordx2 v[234:235], v[250:251], off offset:512 nt
	global_load_dwordx2 v[236:237], v[250:251], off offset:1024 nt
	global_load_dwordx2 v[238:239], v[250:251], off offset:1536 nt
	global_load_dwordx2 v[240:241], v[248:249], off offset:1536 nt
	global_load_dwordx2 v[242:243], v[250:251], off offset:3072 nt
	global_load_dwordx2 v[244:245], v[250:251], off offset:3584 nt
	v_and_b32_e32 v83, 0xffff0000, v46
	v_lshlrev_b32_e32 v78, 16, v56
	v_and_b32_e32 v67, 0xffff0000, v58
	v_and_b32_e32 v66, 0xffff0000, v60
	v_and_b32_e32 v82, 0xffff0000, v56
	v_lshlrev_b32_e32 v94, 16, v57
	v_and_b32_e32 v98, 0xffff0000, v57
	v_lshlrev_b32_e32 v65, 16, v58
	v_lshlrev_b32_e32 v64, 16, v60
	v_pk_mul_f32 v[116:117], v[66:67], v[66:67]
	v_and_b32_e32 v57, 0xffff0000, v106
	v_and_b32_e32 v56, 0xffff0000, v108
	v_lshlrev_b32_e32 v69, 16, v59
	v_lshlrev_b32_e32 v68, 16, v61
	v_and_b32_e32 v71, 0xffff0000, v59
	v_and_b32_e32 v70, 0xffff0000, v61
	v_lshlrev_b32_e32 v73, 16, v62
	v_and_b32_e32 v81, 0xffff0000, v62
	v_lshlrev_b32_e32 v87, 16, v63
	v_and_b32_e32 v97, 0xffff0000, v63
	v_lshlrev_b32_e32 v59, 16, v106
	v_lshlrev_b32_e32 v58, 16, v108
	v_lshlrev_b32_e32 v63, 16, v107
	v_lshlrev_b32_e32 v62, 16, v109
	v_and_b32_e32 v61, 0xffff0000, v107
	v_and_b32_e32 v60, 0xffff0000, v109
	v_pk_fma_f32 v[106:107], v[64:65], v[64:65], v[116:117]
	v_pk_mul_f32 v[108:109], v[56:57], v[56:57]
	v_pk_fma_f32 v[106:107], v[68:69], v[68:69], v[106:107]
	v_pk_fma_f32 v[108:109], v[58:59], v[58:59], v[108:109]
	v_and_b32_e32 v85, 0xffff0000, v76
	v_and_b32_e32 v80, 0xffff0000, v110
	v_and_b32_e32 v84, 0xffff0000, v112
	v_pk_fma_f32 v[134:135], v[70:71], v[70:71], v[106:107]
	v_pk_fma_f32 v[106:107], v[62:63], v[62:63], v[108:109]
	v_lshlrev_b32_e32 v75, 16, v76
	v_lshlrev_b32_e32 v72, 16, v110
	v_lshlrev_b32_e32 v74, 16, v112
	v_pk_fma_f32 v[136:137], v[60:61], v[60:61], v[106:107]
	v_pk_mul_f32 v[106:107], v[80:81], v[80:81]
	v_pk_mul_f32 v[108:109], v[84:85], v[84:85]
	v_lshlrev_b32_e32 v91, 16, v77
	v_lshlrev_b32_e32 v86, 16, v111
	v_lshlrev_b32_e32 v90, 16, v113
	v_pk_fma_f32 v[106:107], v[72:73], v[72:73], v[106:107]
	v_pk_fma_f32 v[108:109], v[74:75], v[74:75], v[108:109]
	v_and_b32_e32 v103, 0xffff0000, v77
	v_and_b32_e32 v96, 0xffff0000, v111
	v_and_b32_e32 v102, 0xffff0000, v113
	v_pk_fma_f32 v[106:107], v[86:87], v[86:87], v[106:107]
	v_pk_fma_f32 v[108:109], v[90:91], v[90:91], v[108:109]
	v_and_b32_e32 v89, 0xffff0000, v104
	v_and_b32_e32 v88, 0xffff0000, v114
	v_pk_fma_f32 v[106:107], v[96:97], v[96:97], v[106:107]
	v_pk_fma_f32 v[108:109], v[102:103], v[102:103], v[108:109]
	v_lshlrev_b32_e32 v77, 16, v104
	v_lshlrev_b32_e32 v76, 16, v114
	v_pk_add_f32 v[106:107], v[106:107], v[108:109]
	v_pk_mul_f32 v[108:109], v[88:89], v[88:89]
	v_lshlrev_b32_e32 v93, 16, v105
	v_lshlrev_b32_e32 v92, 16, v115
	v_pk_fma_f32 v[108:109], v[76:77], v[76:77], v[108:109]
	v_and_b32_e32 v105, 0xffff0000, v105
	v_and_b32_e32 v104, 0xffff0000, v115
	v_pk_fma_f32 v[108:109], v[92:93], v[92:93], v[108:109]
	v_and_b32_e32 v117, 0xffff0000, v120
	v_and_b32_e32 v116, 0xffff0000, v122
	v_pk_fma_f32 v[108:109], v[104:105], v[104:105], v[108:109]
	v_lshlrev_b32_e32 v79, 16, v46
	v_lshlrev_b32_e32 v95, 16, v47
	v_and_b32_e32 v99, 0xffff0000, v47
	v_pk_mul_f32 v[46:47], v[82:83], v[82:83]
	v_lshlrev_b32_e32 v114, 16, v122
	v_lshlrev_b32_e32 v115, 16, v120
	v_pk_add_f32 v[106:107], v[106:107], v[108:109]
	v_pk_mul_f32 v[108:109], v[116:117], v[116:117]
	v_pk_fma_f32 v[46:47], v[78:79], v[78:79], v[46:47]
	v_lshlrev_b32_e32 v118, 16, v123
	v_lshlrev_b32_e32 v119, 16, v121
	v_pk_fma_f32 v[108:109], v[114:115], v[114:115], v[108:109]
	v_pk_fma_f32 v[46:47], v[94:95], v[94:95], v[46:47]
	v_and_b32_e32 v121, 0xffff0000, v121
	v_and_b32_e32 v120, 0xffff0000, v123
	v_pk_fma_f32 v[108:109], v[118:119], v[118:119], v[108:109]
	v_pk_fma_f32 v[46:47], v[98:99], v[98:99], v[46:47]
	v_pk_fma_f32 v[108:109], v[120:121], v[120:121], v[108:109]
	v_lshlrev_b32_e32 v110, 16, v131
	v_pk_add_f32 v[106:107], v[106:107], v[108:109]
	v_mov_b32_e32 v108, v136
	v_mov_b32_e32 v109, v46
	v_pk_add_f32 v[122:123], v[106:107], v[108:109]
	v_and_b32_e32 v109, 0xffff0000, v132
	v_and_b32_e32 v108, 0xffff0000, v130
	v_lshlrev_b32_e32 v107, 16, v132
	v_lshlrev_b32_e32 v106, 16, v130
	v_and_b32_e32 v112, 0xffff0000, v131
	v_pk_mul_f32 v[130:131], v[108:109], v[108:109]
	v_lshlrev_b32_e32 v111, 16, v133
	v_pk_fma_f32 v[130:131], v[106:107], v[106:107], v[130:131]
	v_and_b32_e32 v113, 0xffff0000, v133
	v_pk_fma_f32 v[130:131], v[110:111], v[110:111], v[130:131]
	v_mov_b32_e32 v46, v137
	v_pk_fma_f32 v[130:131], v[112:113], v[112:113], v[130:131]
	v_pk_add_f32 v[46:47], v[122:123], v[46:47]
	v_mov_b32_e32 v122, v130
	v_mov_b32_e32 v123, v134
	v_pk_add_f32 v[46:47], v[46:47], v[122:123]
	v_mov_b32_e32 v134, v131
	v_pk_add_f32 v[46:47], v[46:47], v[134:135]
	ds_bpermute_b32 v123, v55, v47
	ds_bpermute_b32 v122, v55, v46
	global_load_dwordx4 v[130:133], v[100:101], off offset:3072 nt
	global_load_dwordx4 v[134:137], v[178:179], off nt
	global_load_dwordx4 v[138:141], v[178:179], off offset:1024 nt
	global_load_dwordx4 v[142:145], v[178:179], off offset:2048 nt
	global_load_dwordx4 v[146:149], v[178:179], off offset:3072 nt
	global_load_dwordx4 v[150:153], v[180:181], off nt
	global_load_dwordx4 v[154:157], v[180:181], off offset:1024 nt
	global_load_dwordx4 v[158:161], v[180:181], off offset:2048 nt
	global_load_dwordx4 v[162:165], v[180:181], off offset:3072 nt
	s_waitcnt lgkmcnt(0)
	v_pk_add_f32 v[46:47], v[46:47], v[122:123]
	ds_bpermute_b32 v123, v124, v47
	ds_bpermute_b32 v122, v124, v46
	v_mov_b32_e32 v186, v73
	v_mov_b32_e32 v187, v81
	v_mov_b32_e32 v188, v87
	v_mov_b32_e32 v189, v97
	s_waitcnt lgkmcnt(0)
	v_pk_add_f32 v[46:47], v[46:47], v[122:123]
	ds_bpermute_b32 v123, v125, v47
	ds_bpermute_b32 v122, v125, v46
	v_mov_b32_e32 v73, v80
	v_mov_b32_e32 v87, v96
	s_waitcnt lgkmcnt(0)
	v_pk_add_f32 v[46:47], v[46:47], v[122:123]
	ds_bpermute_b32 v123, v126, v47
	ds_bpermute_b32 v122, v126, v46
	s_waitcnt lgkmcnt(0)
	v_pk_add_f32 v[44:45], v[46:47], v[122:123]
	ds_bpermute_b32 v47, v127, v45
	ds_bpermute_b32 v46, v127, v44
	v_add_co_u32_e32 v122, vcc, s3, v180
	s_waitcnt lgkmcnt(0)
	v_pk_add_f32 v[44:45], v[44:45], v[46:47]
	ds_bpermute_b32 v47, v128, v45
	ds_bpermute_b32 v46, v128, v44
	v_addc_co_u32_e32 v123, vcc, 0, v181, vcc
	s_waitcnt lgkmcnt(0)
	v_pk_add_f32 v[44:45], v[44:45], v[46:47]
	s_nop 0
	v_pk_fma_f32 v[182:183], v[44:45], s[2:3], v[54:55] op_sel_hi:[1,0,0]
	s_nop 0
	v_mul_f32_e32 v44, 0x4b800000, v183
	v_cmp_gt_f32_e32 vcc, s5, v183
	s_nop 1
	v_cndmask_b32_e32 v44, v183, v44, vcc
	v_rsq_f32_e32 v49, v44
	global_load_dwordx4 v[166:169], v[122:123], off nt
	global_load_dwordx4 v[170:173], v[122:123], off offset:1024 nt
	global_load_dwordx4 v[174:177], v[122:123], off offset:2048 nt
	global_load_dwordx4 v[44:47], v[122:123], off offset:3072 nt
	v_mul_f32_e32 v129, 0x45800000, v49
	v_cndmask_b32_e32 v184, v49, v129, vcc
	v_pk_mul_f32 v[186:187], v[186:187], v[184:185] op_sel_hi:[1,0]
	v_pk_mul_f32 v[188:189], v[188:189], v[184:185] op_sel_hi:[1,0]
	s_waitcnt vmcnt(29)
	v_pk_fma_f32 v[40:41], v[0:1], v[186:187], v[40:41]
	v_pk_fma_f32 v[42:43], v[2:3], v[188:189], v[42:43]
	global_store_dwordx4 v[100:101], v[40:43], off nt
	v_cmp_gt_f32_e32 vcc, s5, v182
	s_nop 0
	v_mov_b32_e32 v40, v75
	v_mov_b32_e32 v41, v85
	v_mov_b32_e32 v42, v91
	v_mov_b32_e32 v43, v103
	v_pk_mul_f32 v[40:41], v[40:41], v[184:185] op_sel_hi:[1,0]
	v_pk_mul_f32 v[42:43], v[42:43], v[184:185] op_sel_hi:[1,0]
	v_pk_fma_f32 v[36:37], v[4:5], v[40:41], v[36:37]
	v_pk_fma_f32 v[38:39], v[6:7], v[42:43], v[38:39]
	global_store_dwordx4 v[100:101], v[36:39], off offset:1024 nt
	v_mov_b32_e32 v75, v84
	v_mov_b32_e32 v91, v102
	v_mov_b32_e32 v36, v77
	v_mov_b32_e32 v37, v89
	v_mov_b32_e32 v38, v93
	v_mov_b32_e32 v39, v105
	v_pk_mul_f32 v[36:37], v[36:37], v[184:185] op_sel_hi:[1,0]
	v_pk_mul_f32 v[38:39], v[38:39], v[184:185] op_sel_hi:[1,0]
	v_pk_fma_f32 v[32:33], v[8:9], v[36:37], v[32:33]
	v_pk_fma_f32 v[34:35], v[10:11], v[38:39], v[34:35]
	global_store_dwordx4 v[100:101], v[32:35], off offset:2048 nt
	v_mul_f32_e32 v36, 0x4b800000, v182
	v_cndmask_b32_e32 v36, v182, v36, vcc
	v_mov_b32_e32 v32, v115
	v_mov_b32_e32 v33, v117
	v_mov_b32_e32 v34, v119
	v_mov_b32_e32 v35, v121
	v_pk_mul_f32 v[32:33], v[32:33], v[184:185] op_sel_hi:[1,0]
	v_pk_mul_f32 v[34:35], v[34:35], v[184:185] op_sel_hi:[1,0]
	s_waitcnt vmcnt(15)
	v_pk_fma_f32 v[32:33], v[12:13], v[32:33], v[130:131]
	v_pk_fma_f32 v[34:35], v[14:15], v[34:35], v[132:133]
	global_store_dwordx4 v[100:101], v[32:35], off offset:3072 nt
	v_rsq_f32_e32 v36, v36
	v_mov_b32_e32 v77, v88
	v_mov_b32_e32 v32, v78
	v_mov_b32_e32 v33, v82
	v_mov_b32_e32 v34, v94
	v_mov_b32_e32 v35, v98
	v_pk_mul_f32 v[32:33], v[32:33], v[184:185] op_sel_hi:[1,0]
	v_pk_mul_f32 v[34:35], v[34:35], v[184:185] op_sel_hi:[1,0]
	s_waitcnt vmcnt(15)
	v_pk_fma_f32 v[32:33], v[16:17], v[32:33], v[134:135]
	v_pk_fma_f32 v[34:35], v[18:19], v[34:35], v[136:137]
	v_mov_b32_e32 v82, v79
	v_mov_b32_e32 v98, v95
	global_store_dwordx4 v[178:179], v[32:35], off nt
	v_mov_b32_e32 v93, v104
	v_mov_b32_e32 v115, v116
	v_pk_mul_f32 v[32:33], v[82:83], v[184:185] op_sel_hi:[1,0]
	v_pk_mul_f32 v[34:35], v[98:99], v[184:185] op_sel_hi:[1,0]
	s_waitcnt vmcnt(15)
	v_pk_fma_f32 v[32:33], v[20:21], v[32:33], v[138:139]
	v_pk_fma_f32 v[34:35], v[22:23], v[34:35], v[140:141]
	global_store_dwordx4 v[178:179], v[32:35], off offset:1024 nt
	v_mov_b32_e32 v119, v120
	s_nop 0
	v_mov_b32_e32 v32, v64
	v_mov_b32_e32 v33, v66
	v_mov_b32_e32 v34, v68
	v_mov_b32_e32 v35, v70
	v_pk_mul_f32 v[32:33], v[32:33], v[184:185] op_sel_hi:[1,0]
	v_pk_mul_f32 v[34:35], v[34:35], v[184:185] op_sel_hi:[1,0]
	s_waitcnt vmcnt(15)
	v_pk_fma_f32 v[32:33], v[24:25], v[32:33], v[142:143]
	v_pk_fma_f32 v[34:35], v[26:27], v[34:35], v[144:145]
	v_mov_b32_e32 v66, v65
	v_mov_b32_e32 v70, v69
	global_store_dwordx4 v[178:179], v[32:35], off offset:2048 nt
	s_nop 1
	v_pk_mul_f32 v[32:33], v[66:67], v[184:185] op_sel_hi:[1,0]
	v_pk_mul_f32 v[34:35], v[70:71], v[184:185] op_sel_hi:[1,0]
	s_waitcnt vmcnt(15)
	v_pk_fma_f32 v[32:33], v[28:29], v[32:33], v[146:147]
	v_pk_fma_f32 v[34:35], v[30:31], v[34:35], v[148:149]
	global_store_dwordx4 v[178:179], v[32:35], off offset:3072 nt
	s_nop 1
	v_mul_f32_e32 v32, 0x45800000, v36
	v_cndmask_b32_e32 v36, v36, v32, vcc
	v_pk_mul_f32 v[32:33], v[72:73], v[36:37] op_sel_hi:[1,0]
	v_pk_mul_f32 v[34:35], v[86:87], v[36:37] op_sel_hi:[1,0]
	s_waitcnt vmcnt(15)
	v_pk_fma_f32 v[32:33], v[0:1], v[32:33], v[150:151]
	v_pk_fma_f32 v[34:35], v[2:3], v[34:35], v[152:153]
	global_store_dwordx4 v[180:181], v[32:35], off nt
	v_cmp_lt_i32_e32 vcc, s6, v48
	s_or_b64 s[0:1], vcc, s[0:1]
	v_pk_mul_f32 v[32:33], v[74:75], v[36:37] op_sel_hi:[1,0]
	v_pk_mul_f32 v[34:35], v[90:91], v[36:37] op_sel_hi:[1,0]
	s_waitcnt vmcnt(15)
	v_pk_fma_f32 v[32:33], v[4:5], v[32:33], v[154:155]
	v_pk_fma_f32 v[34:35], v[6:7], v[34:35], v[156:157]
	global_store_dwordx4 v[180:181], v[32:35], off offset:1024 nt
	s_nop 1
	v_pk_mul_f32 v[32:33], v[76:77], v[36:37] op_sel_hi:[1,0]
	v_pk_mul_f32 v[34:35], v[92:93], v[36:37] op_sel_hi:[1,0]
	s_waitcnt vmcnt(15)
	v_pk_fma_f32 v[32:33], v[8:9], v[32:33], v[158:159]
	v_pk_fma_f32 v[34:35], v[10:11], v[34:35], v[160:161]
	global_store_dwordx4 v[180:181], v[32:35], off offset:2048 nt
	s_nop 1
	v_pk_mul_f32 v[32:33], v[114:115], v[36:37] op_sel_hi:[1,0]
	v_pk_mul_f32 v[34:35], v[118:119], v[36:37] op_sel_hi:[1,0]
	s_waitcnt vmcnt(15)
	v_pk_fma_f32 v[32:33], v[12:13], v[32:33], v[162:163]
	v_pk_fma_f32 v[34:35], v[14:15], v[34:35], v[164:165]
	global_store_dwordx4 v[180:181], v[32:35], off offset:3072 nt
	s_nop 1
	v_mov_b32_e32 v32, v58
	v_mov_b32_e32 v33, v56
	v_mov_b32_e32 v34, v62
	v_mov_b32_e32 v35, v60
	v_pk_mul_f32 v[32:33], v[32:33], v[36:37] op_sel_hi:[1,0]
	v_pk_mul_f32 v[34:35], v[34:35], v[36:37] op_sel_hi:[1,0]
	s_waitcnt vmcnt(15)
	v_pk_fma_f32 v[32:33], v[16:17], v[32:33], v[166:167]
	v_pk_fma_f32 v[34:35], v[18:19], v[34:35], v[168:169]
	v_mov_b32_e32 v56, v59
	v_mov_b32_e32 v60, v63
	global_store_dwordx4 v[122:123], v[32:35], off nt
	s_nop 1
	v_pk_mul_f32 v[32:33], v[56:57], v[36:37] op_sel_hi:[1,0]
	v_pk_mul_f32 v[34:35], v[60:61], v[36:37] op_sel_hi:[1,0]
	s_waitcnt vmcnt(15)
	v_pk_fma_f32 v[32:33], v[20:21], v[32:33], v[170:171]
	v_pk_fma_f32 v[34:35], v[22:23], v[34:35], v[172:173]
	global_store_dwordx4 v[122:123], v[32:35], off offset:1024 nt
	s_nop 1
	v_mov_b32_e32 v32, v106
	v_mov_b32_e32 v33, v108
	v_mov_b32_e32 v34, v110
	v_mov_b32_e32 v35, v112
	v_pk_mul_f32 v[32:33], v[32:33], v[36:37] op_sel_hi:[1,0]
	v_pk_mul_f32 v[34:35], v[34:35], v[36:37] op_sel_hi:[1,0]
	s_waitcnt vmcnt(15)
	v_pk_fma_f32 v[32:33], v[24:25], v[32:33], v[174:175]
	v_pk_fma_f32 v[34:35], v[26:27], v[34:35], v[176:177]
	v_mov_b32_e32 v108, v107
	v_mov_b32_e32 v112, v111
	global_store_dwordx4 v[122:123], v[32:35], off offset:2048 nt
	s_nop 1
	v_pk_mul_f32 v[32:33], v[108:109], v[36:37] op_sel_hi:[1,0]
	v_pk_mul_f32 v[34:35], v[112:113], v[36:37] op_sel_hi:[1,0]
	s_waitcnt vmcnt(15)
	v_pk_fma_f32 v[32:33], v[28:29], v[32:33], v[44:45]
	v_pk_fma_f32 v[34:35], v[30:31], v[34:35], v[46:47]
	global_store_dwordx4 v[122:123], v[32:35], off offset:3072 nt
	s_andn2_b64 exec, exec, s[0:1]
	s_cbranch_execnz .LBB0_1491
